# first-touch small inputs (lambda vectors, sub-layer-norm gains, final gains) touched before the preceding seam so that their cold miss overlaps the seam
# baseline (speedup 1.0000x reference)
.LBB0_899:
	v_readlane_b32 s98, v255, 45
	v_readlane_b32 s99, v255, 46
	v_and_b32_e32 v142, 31, v204
	v_lshlrev_b32_e32 v142, 7, v142
	s_nop 4
	global_load_dword v143, v142, s[98:99]
	v_readlane_b32 s0, v255, 59
	s_add_i32 s19, s0, 3
	s_cmp_ge_i32 s19, s87
	s_cbranch_scc1 .LBB0_953
	s_waitcnt vmcnt(0)
	v_readlane_b32 s12, v253, 2
	v_readlane_b32 s13, v253, 3
	s_waitcnt vmcnt(0) lgkmcnt(0)
	s_barrier
	s_and_saveexec_b64 s[0:1], s[12:13]
	s_cbranch_execz .LBB0_952
	v_readlane_b32 s12, v255, 50
	s_waitcnt vmcnt(0) expcnt(0) lgkmcnt(0)
	s_nop 0
	v_mov_b32_e32 v0, s12
	ds_read_b32 v3, v0
	v_readlane_b32 s12, v255, 55
	s_waitcnt lgkmcnt(0)
	v_cmp_ne_u32_e32 vcc, 0, v3
	v_mov_b32_e32 v0, s12
	ds_read_b32 v2, v0
	s_cbranch_vccnz .LBB0_916
	v_readlane_b32 s22, v253, 0
	v_readlane_b32 s23, v253, 1
	s_load_dwordx2 s[20:21], s[22:23], 0x4
	s_waitcnt lgkmcnt(0)
	s_mul_i32 s20, s20, s3
	s_mul_i32 s20, s20, s21
	s_mov_b32 s21, 1
	s_branch .LBB0_904

.LBB0_1287:
	v_mov_b32_e32 v8, v204
	v_and_b32_e32 v30, 63, v204
	v_lshlrev_b32_e32 v30, 2, v30
	global_load_dword v31, v30, s[56:57]
	global_load_dword v31, v30, s[56:57] offset:256
	global_load_dword v31, v30, s[56:57] offset:512
	global_load_dword v31, v30, s[56:57] offset:768
	global_load_dword v31, v1, s[58:59]
	global_load_dword v31, v1, s[58:59] offset:128
	global_load_dword v31, v1, s[58:59] offset:256
	global_load_dword v31, v1, s[58:59] offset:384
	s_waitcnt vmcnt(0)
	s_waitcnt vmcnt(0)
	s_barrier
	v_readlane_b32 s12, v253, 25
	v_readfirstlane_b32 s0, v8
	s_ashr_i32 s19, s0, 6
	v_bfe_u32 v0, v8, 5, 1
	v_lshl_or_b32 v9, s19, 5, v0
	v_and_b32_e32 v0, 39, v8
	v_cmp_eq_u32_e64 s[0:1], 0, v0
	v_and_b32_e32 v0, 1, v8
	v_and_b32_e32 v4, 31, v8
	s_lshl_b32 s19, s19, 4
	v_lshlrev_b32_e32 v0, 2, v0
	v_readlane_b32 s13, v253, 26
	s_add_i32 s19, s19, 0
	v_bfe_u32 v6, v8, 1, 4
	v_lshl_add_u64 v[2:3], s[12:13], 0, v[0:1]
	v_lshlrev_b32_e32 v0, 4, v4
	s_mov_b32 s20, 0
	v_cmp_gt_i32_e64 s[38:39], 4, v8
	v_lshl_add_u32 v10, v8, 2, 0
	v_lshl_add_u64 v[4:5], s[78:79], 0, v[0:1]
	v_add_u32_e32 v0, s19, v6
	s_mov_b32 s21, 0
	s_mov_b32 s19, 0
	s_branch .LBB0_1291
